# rsq in all GEMM epilogues + all 8 row-stat loads in one batch in both MLP-up epilogues
# baseline (speedup 1.0000x reference)
.LBB0_614:
	v_lshl_add_u32 v248, s6, 8, v169
	v_mov_b32_e32 v249, 0
	v_lshl_add_u64 v[248:249], v[248:249], 3, s[30:31]
	global_load_dwordx2 v[234:235], v[248:249], off
	global_load_dwordx2 v[236:237], v[248:249], off offset:128
	global_load_dwordx2 v[238:239], v[248:249], off offset:256
	global_load_dwordx2 v[240:241], v[248:249], off offset:384
	global_load_dwordx2 v[242:243], v[248:249], off offset:1024
	global_load_dwordx2 v[244:245], v[248:249], off offset:1152
	global_load_dwordx2 v[246:247], v[248:249], off offset:1280
	global_load_dwordx2 v[248:249], v[248:249], off offset:1408
	v_lshl_add_u32 v188, s6, 8, v169
	v_ashrrev_i32_e32 v189, 31, v188
	v_lshl_add_u64 v[128:129], v[188:189], 3, s[30:31]
	v_or_b32_e32 v194, 16, v188
	v_ashrrev_i32_e32 v195, 31, v194
	v_or_b32_e32 v192, 32, v188
	v_lshl_add_u64 v[128:129], v[194:195], 3, s[30:31]
	v_ashrrev_i32_e32 v193, 31, v192
	v_lshl_add_u64 v[130:131], v[192:193], 3, s[30:31]
	v_lshl_or_b32 v212, s7, 8, v187
	v_ashrrev_i32_e32 v213, 31, v212
	v_or_b32_e32 v184, 48, v188
	v_add_u32_e32 v180, 0x80, v188
	v_lshlrev_b64 v[128:129], 2, v[212:213]
	v_ashrrev_i32_e32 v185, 31, v184
	v_ashrrev_i32_e32 v181, 31, v180
	v_lshl_add_u64 v[130:131], s[68:69], 0, v[128:129]
	v_lshl_add_u64 v[136:137], s[70:71], 0, v[128:129]
	v_lshl_add_u64 v[200:201], v[184:185], 3, s[30:31]
	v_lshl_add_u64 v[202:203], v[180:181], 3, s[30:31]
	global_load_dwordx4 v[148:151], v[130:131], off offset:16
	global_load_dwordx4 v[156:159], v[130:131], off
	global_load_dwordx4 v[144:147], v[136:137], off offset:16
	global_load_dwordx4 v[152:155], v[136:137], off
	global_load_dwordx4 v[132:135], v[130:131], off offset:528
	global_load_dwordx4 v[140:143], v[130:131], off offset:512
	s_nop 0
	global_load_dwordx4 v[128:131], v[136:137], off offset:528
	s_nop 0
	global_load_dwordx4 v[136:139], v[136:137], off offset:512
	s_nop 0
	s_nop 0
	v_lshlrev_b64 v[212:213], 1, v[212:213]
	s_waitcnt vmcnt(0)
	v_pk_mul_f32 v[218:219], v[234:235], s[38:39] op_sel_hi:[1,0]
	s_nop 0
	v_fma_f32 v182, -v218, v218, v219
	v_add_f32_e32 v182, 0x3727c5ac, v182
	v_pk_mul_f32 v[208:209], v[236:237], s[38:39] op_sel_hi:[1,0]
	v_pk_mul_f32 v[198:199], v[238:239], s[38:39] op_sel_hi:[1,0]
	v_fma_f32 v183, -v208, v208, v209
	v_fma_f32 v186, -v198, v198, v199
	v_add_f32_e32 v183, 0x3727c5ac, v183
	v_add_f32_e32 v186, 0x3727c5ac, v186
	v_pk_mul_f32 v[206:207], v[242:243], s[38:39] op_sel_hi:[1,0]
	s_nop 0
	v_rsq_f32_e32 v222, v182
	v_rsq_f32_e32 v214, v183
	v_pk_mul_f32 v[202:203], v[240:241], s[38:39] op_sel_hi:[1,0]
	v_fma_f32 v200, -v202, v202, v203
	v_add_f32_e32 v200, 0x3727c5ac, v200
	v_rsq_f32_e32 v216, v200
	v_add_u32_e32 v182, 0x90, v188
	v_ashrrev_i32_e32 v183, 31, v182
	v_lshl_add_u64 v[182:183], v[182:183], 3, s[30:31]
	v_rsq_f32_e32 v220, v186
	v_pk_fma_f32 v[104:105], v[148:149], v[208:209], v[104:105] op_sel_hi:[1,0,1] neg_lo:[1,0,0] neg_hi:[1,0,0]
	v_pk_fma_f32 v[108:109], v[156:157], v[208:209], v[108:109] op_sel_hi:[1,0,1] neg_lo:[1,0,0] neg_hi:[1,0,0]
	v_pk_fma_f32 v[104:105], v[104:105], v[214:215], v[144:145] op_sel_hi:[1,0,1]
	v_add_u32_e32 v190, 0xa0, v188
	v_ashrrev_i32_e32 v191, 31, v190
	v_lshl_add_u64 v[190:191], v[190:191], 3, s[30:31]
	v_add_u32_e32 v200, 0xb0, v188
	v_ashrrev_i32_e32 v201, 31, v200
	v_lshl_add_u64 v[200:201], v[200:201], 3, s[30:31]
	v_fma_f32 v200, -v206, v206, v207
	v_add_f32_e32 v200, 0x3727c5ac, v200
	v_rsq_f32_e32 v210, v200
	v_lshlrev_b64 v[188:189], 13, v[188:189]
	v_lshl_add_u64 v[188:189], s[24:25], 0, v[188:189]
	v_lshl_add_u64 v[188:189], v[188:189], 0, v[212:213]
	v_pk_fma_f32 v[108:109], v[108:109], v[214:215], v[152:153] op_sel_hi:[1,0,1]
	v_max_f32_e32 v104, 0, v104
	v_pk_mul_f32 v[200:201], v[244:245], s[38:39] op_sel_hi:[1,0]
	v_fma_f32 v182, -v200, v200, v201
	v_add_f32_e32 v182, 0x3727c5ac, v182
	v_max_f32_e32 v105, 0, v105
	v_max_f32_e32 v108, 0, v108
	v_max_f32_e32 v109, 0, v109
	v_pk_fma_f32 v[96:97], v[132:133], v[208:209], v[96:97] op_sel_hi:[1,0,1] neg_lo:[1,0,0] neg_hi:[1,0,0]
	v_pk_mul_f32 v[108:109], v[108:109], v[108:109]
	v_pk_mul_f32 v[190:191], v[246:247], s[38:39] op_sel_hi:[1,0]
	v_pk_fma_f32 v[100:101], v[140:141], v[208:209], v[100:101] op_sel_hi:[1,0,1] neg_lo:[1,0,0] neg_hi:[1,0,0]
	v_fma_f32 v204, -v190, v190, v191
	v_add_f32_e32 v204, 0x3727c5ac, v204
	v_rsq_f32_e32 v196, v204
	v_pk_fma_f32 v[96:97], v[96:97], v[214:215], v[128:129] op_sel_hi:[1,0,1]
	v_pk_fma_f32 v[100:101], v[100:101], v[214:215], v[136:137] op_sel_hi:[1,0,1]
	v_max_f32_e32 v96, 0, v96
	v_max_f32_e32 v97, 0, v97
	v_rsq_f32_e32 v204, v182
	v_pk_mul_f32 v[182:183], v[248:249], s[38:39] op_sel_hi:[1,0]
	v_fma_f32 v224, -v182, v182, v183
	v_add_f32_e32 v224, 0x3727c5ac, v224
	v_rsq_f32_e32 v186, v224
	v_max_f32_e32 v100, 0, v100
	v_max_f32_e32 v101, 0, v101
	v_pk_fma_f32 v[88:89], v[148:149], v[198:199], v[88:89] op_sel_hi:[1,0,1] neg_lo:[1,0,0] neg_hi:[1,0,0]
	v_pk_mul_f32 v[100:101], v[100:101], v[100:101]
	v_pk_fma_f32 v[92:93], v[156:157], v[198:199], v[92:93] op_sel_hi:[1,0,1] neg_lo:[1,0,0] neg_hi:[1,0,0]
	v_pk_fma_f32 v[88:89], v[88:89], v[220:221], v[144:145] op_sel_hi:[1,0,1]
	v_pk_fma_f32 v[92:93], v[92:93], v[220:221], v[152:153] op_sel_hi:[1,0,1]
	v_max_f32_e32 v88, 0, v88
	v_pk_fma_f32 v[224:225], v[156:157], v[218:219], v[124:125] op_sel_hi:[1,0,1] neg_lo:[1,0,0] neg_hi:[1,0,0]
	v_xor_b32_e32 v125, 0x80000000, v159
	v_xor_b32_e32 v124, 0x80000000, v158
	v_pk_fma_f32 v[158:159], v[224:225], v[222:223], v[152:153] op_sel_hi:[1,0,1]
	v_pk_fma_f32 v[224:225], v[148:149], v[218:219], v[120:121] op_sel_hi:[1,0,1] neg_lo:[1,0,0] neg_hi:[1,0,0]
	v_xor_b32_e32 v121, 0x80000000, v151
	v_xor_b32_e32 v120, 0x80000000, v150
	v_pk_fma_f32 v[126:127], v[124:125], v[218:219], v[126:127] op_sel_hi:[1,0,1]
	v_pk_fma_f32 v[122:123], v[120:121], v[218:219], v[122:123] op_sel_hi:[1,0,1]
	v_pk_fma_f32 v[126:127], v[126:127], v[222:223], v[154:155] op_sel_hi:[1,0,1]
	v_pk_fma_f32 v[122:123], v[122:123], v[222:223], v[146:147] op_sel_hi:[1,0,1]
	v_max_f32_e32 v126, 0, v126
	v_max_f32_e32 v122, 0, v122
	v_max_f32_e32 v127, 0, v127
	v_max_f32_e32 v123, 0, v123
	v_pk_mul_f32 v[126:127], v[126:127], v[126:127]
	v_pk_mul_f32 v[122:123], v[122:123], v[122:123]
	v_pk_fma_f32 v[150:151], v[224:225], v[222:223], v[144:145] op_sel_hi:[1,0,1]
	v_cvt_pk_bf16_f32 v225, v126, v127
	v_cvt_pk_bf16_f32 v227, v122, v123
	v_pk_fma_f32 v[122:123], v[140:141], v[218:219], v[116:117] op_sel_hi:[1,0,1] neg_lo:[1,0,0] neg_hi:[1,0,0]
	v_xor_b32_e32 v117, 0x80000000, v143
	v_xor_b32_e32 v116, 0x80000000, v142
	v_pk_fma_f32 v[126:127], v[132:133], v[218:219], v[112:113] op_sel_hi:[1,0,1] neg_lo:[1,0,0] neg_hi:[1,0,0]
	v_xor_b32_e32 v113, 0x80000000, v135
	v_xor_b32_e32 v112, 0x80000000, v134
	v_pk_fma_f32 v[118:119], v[116:117], v[218:219], v[118:119] op_sel_hi:[1,0,1]
	v_pk_fma_f32 v[114:115], v[112:113], v[218:219], v[114:115] op_sel_hi:[1,0,1]
	v_max_f32_e32 v158, 0, v158
	v_max_f32_e32 v150, 0, v150
	v_max_f32_e32 v159, 0, v159
	v_max_f32_e32 v151, 0, v151
	v_pk_fma_f32 v[118:119], v[118:119], v[222:223], v[138:139] op_sel_hi:[1,0,1]
	v_pk_fma_f32 v[114:115], v[114:115], v[222:223], v[130:131] op_sel_hi:[1,0,1]
	v_pk_mul_f32 v[158:159], v[158:159], v[158:159]
	v_pk_mul_f32 v[150:151], v[150:151], v[150:151]
	v_pk_fma_f32 v[122:123], v[122:123], v[222:223], v[136:137] op_sel_hi:[1,0,1]
	v_max_f32_e32 v118, 0, v118
	v_max_f32_e32 v114, 0, v114
	v_max_f32_e32 v119, 0, v119
	v_max_f32_e32 v115, 0, v115
	v_pk_fma_f32 v[110:111], v[124:125], v[208:209], v[110:111] op_sel_hi:[1,0,1]
	v_pk_fma_f32 v[106:107], v[120:121], v[208:209], v[106:107] op_sel_hi:[1,0,1]
	v_cvt_pk_bf16_f32 v224, v158, v159
	v_cvt_pk_bf16_f32 v226, v150, v151
	v_max_f32_e32 v122, 0, v122
	v_max_f32_e32 v123, 0, v123
	v_pk_mul_f32 v[118:119], v[118:119], v[118:119]
	v_pk_mul_f32 v[114:115], v[114:115], v[114:115]
	v_pk_fma_f32 v[110:111], v[110:111], v[214:215], v[154:155] op_sel_hi:[1,0,1]
	v_pk_fma_f32 v[106:107], v[106:107], v[214:215], v[146:147] op_sel_hi:[1,0,1]
	global_store_dwordx4 v[188:189], v[224:227], off nt
	v_pk_fma_f32 v[126:127], v[126:127], v[222:223], v[128:129] op_sel_hi:[1,0,1]
	v_pk_mul_f32 v[122:123], v[122:123], v[122:123]
	v_cvt_pk_bf16_f32 v223, v118, v119
	v_cvt_pk_bf16_f32 v225, v114, v115
	v_lshlrev_b64 v[114:115], 13, v[194:195]
	v_pk_mul_f32 v[118:119], v[104:105], v[104:105]
	v_max_f32_e32 v104, 0, v110
	v_max_f32_e32 v106, 0, v106
	v_max_f32_e32 v105, 0, v111
	v_max_f32_e32 v107, 0, v107
	v_cvt_pk_bf16_f32 v222, v122, v123
	v_lshl_add_u64 v[114:115], s[24:25], 0, v[114:115]
	v_pk_mul_f32 v[110:111], v[104:105], v[104:105]
	v_pk_mul_f32 v[122:123], v[106:107], v[106:107]
	v_pk_fma_f32 v[102:103], v[116:117], v[208:209], v[102:103] op_sel_hi:[1,0,1]
	v_pk_fma_f32 v[98:99], v[112:113], v[208:209], v[98:99] op_sel_hi:[1,0,1]
	v_lshl_add_u64 v[114:115], v[114:115], 0, v[212:213]
	v_cvt_pk_bf16_f32 v104, v108, v109
	v_cvt_pk_bf16_f32 v105, v110, v111
	v_cvt_pk_bf16_f32 v106, v118, v119
	v_cvt_pk_bf16_f32 v107, v122, v123
	v_pk_fma_f32 v[102:103], v[102:103], v[214:215], v[138:139] op_sel_hi:[1,0,1]
	v_pk_fma_f32 v[98:99], v[98:99], v[214:215], v[130:131] op_sel_hi:[1,0,1]
	global_store_dwordx4 v[114:115], v[104:107], off nt
	v_max_f32_e32 v98, 0, v98
	v_max_f32_e32 v99, 0, v99
	v_pk_mul_f32 v[104:105], v[96:97], v[96:97]
	v_max_f32_e32 v96, 0, v102
	v_max_f32_e32 v97, 0, v103
	v_pk_mul_f32 v[102:103], v[96:97], v[96:97]
	v_pk_mul_f32 v[106:107], v[98:99], v[98:99]
	v_pk_fma_f32 v[94:95], v[124:125], v[198:199], v[94:95] op_sel_hi:[1,0,1]
	v_pk_fma_f32 v[90:91], v[120:121], v[198:199], v[90:91] op_sel_hi:[1,0,1]
	v_cvt_pk_bf16_f32 v96, v100, v101
	v_cvt_pk_bf16_f32 v97, v102, v103
	v_cvt_pk_bf16_f32 v98, v104, v105
	v_cvt_pk_bf16_f32 v99, v106, v107
	v_pk_fma_f32 v[94:95], v[94:95], v[220:221], v[154:155] op_sel_hi:[1,0,1]
	v_pk_fma_f32 v[90:91], v[90:91], v[220:221], v[146:147] op_sel_hi:[1,0,1]
	v_max_f32_e32 v89, 0, v89
	global_store_dwordx4 v[114:115], v[96:99], off offset:256 nt
	v_max_f32_e32 v92, 0, v92
	v_max_f32_e32 v93, 0, v93
	v_lshlrev_b64 v[96:97], 13, v[192:193]
	v_pk_mul_f32 v[98:99], v[88:89], v[88:89]
	v_max_f32_e32 v88, 0, v94
	v_max_f32_e32 v90, 0, v90
	v_max_f32_e32 v89, 0, v95
	v_max_f32_e32 v91, 0, v91
	v_pk_fma_f32 v[80:81], v[132:133], v[198:199], v[80:81] op_sel_hi:[1,0,1] neg_lo:[1,0,0] neg_hi:[1,0,0]
	v_lshl_add_u64 v[96:97], s[24:25], 0, v[96:97]
	v_pk_mul_f32 v[92:93], v[92:93], v[92:93]
	v_pk_mul_f32 v[94:95], v[88:89], v[88:89]
	v_pk_mul_f32 v[100:101], v[90:91], v[90:91]
	v_pk_fma_f32 v[84:85], v[140:141], v[198:199], v[84:85] op_sel_hi:[1,0,1] neg_lo:[1,0,0] neg_hi:[1,0,0]
	v_pk_fma_f32 v[86:87], v[116:117], v[198:199], v[86:87] op_sel_hi:[1,0,1]
	v_pk_fma_f32 v[82:83], v[112:113], v[198:199], v[82:83] op_sel_hi:[1,0,1]
	v_pk_fma_f32 v[80:81], v[80:81], v[220:221], v[128:129] op_sel_hi:[1,0,1]
	v_lshl_add_u64 v[96:97], v[96:97], 0, v[212:213]
	v_cvt_pk_bf16_f32 v88, v92, v93
	v_cvt_pk_bf16_f32 v89, v94, v95
	v_cvt_pk_bf16_f32 v90, v98, v99
	v_cvt_pk_bf16_f32 v91, v100, v101
	v_pk_fma_f32 v[86:87], v[86:87], v[220:221], v[138:139] op_sel_hi:[1,0,1]
	v_pk_fma_f32 v[84:85], v[84:85], v[220:221], v[136:137] op_sel_hi:[1,0,1]
	v_pk_fma_f32 v[82:83], v[82:83], v[220:221], v[130:131] op_sel_hi:[1,0,1]
	v_max_f32_e32 v80, 0, v80
	v_max_f32_e32 v81, 0, v81
	global_store_dwordx4 v[96:97], v[88:91], off nt
	v_max_f32_e32 v84, 0, v84
	v_max_f32_e32 v85, 0, v85
	v_pk_mul_f32 v[88:89], v[80:81], v[80:81]
	v_max_f32_e32 v80, 0, v86
	v_max_f32_e32 v82, 0, v82
	v_max_f32_e32 v81, 0, v87
	v_max_f32_e32 v83, 0, v83
	v_pk_fma_f32 v[72:73], v[148:149], v[202:203], v[72:73] op_sel_hi:[1,0,1] neg_lo:[1,0,0] neg_hi:[1,0,0]
	v_pk_mul_f32 v[84:85], v[84:85], v[84:85]
	v_pk_mul_f32 v[86:87], v[80:81], v[80:81]
	v_pk_mul_f32 v[90:91], v[82:83], v[82:83]
	v_pk_fma_f32 v[76:77], v[156:157], v[202:203], v[76:77] op_sel_hi:[1,0,1] neg_lo:[1,0,0] neg_hi:[1,0,0]
	v_pk_fma_f32 v[78:79], v[124:125], v[202:203], v[78:79] op_sel_hi:[1,0,1]
	v_pk_fma_f32 v[74:75], v[120:121], v[202:203], v[74:75] op_sel_hi:[1,0,1]
	v_pk_fma_f32 v[72:73], v[72:73], v[216:217], v[144:145] op_sel_hi:[1,0,1]
	v_cvt_pk_bf16_f32 v80, v84, v85
	v_cvt_pk_bf16_f32 v81, v86, v87
	v_cvt_pk_bf16_f32 v82, v88, v89
	v_cvt_pk_bf16_f32 v83, v90, v91
	v_pk_fma_f32 v[78:79], v[78:79], v[216:217], v[154:155] op_sel_hi:[1,0,1]
	v_pk_fma_f32 v[76:77], v[76:77], v[216:217], v[152:153] op_sel_hi:[1,0,1]
	v_pk_fma_f32 v[74:75], v[74:75], v[216:217], v[146:147] op_sel_hi:[1,0,1]
	v_max_f32_e32 v72, 0, v72
	v_max_f32_e32 v73, 0, v73
	global_store_dwordx4 v[96:97], v[80:83], off offset:256 nt
	v_max_f32_e32 v76, 0, v76
	v_max_f32_e32 v77, 0, v77
	v_lshlrev_b64 v[80:81], 13, v[184:185]
	v_pk_mul_f32 v[82:83], v[72:73], v[72:73]
	v_max_f32_e32 v72, 0, v78
	v_max_f32_e32 v74, 0, v74
	v_max_f32_e32 v73, 0, v79
	v_max_f32_e32 v75, 0, v75
	v_pk_fma_f32 v[64:65], v[132:133], v[202:203], v[64:65] op_sel_hi:[1,0,1] neg_lo:[1,0,0] neg_hi:[1,0,0]
	v_lshl_add_u64 v[80:81], s[24:25], 0, v[80:81]
	v_pk_mul_f32 v[76:77], v[76:77], v[76:77]
	v_pk_mul_f32 v[78:79], v[72:73], v[72:73]
	v_pk_mul_f32 v[84:85], v[74:75], v[74:75]
	v_pk_fma_f32 v[68:69], v[140:141], v[202:203], v[68:69] op_sel_hi:[1,0,1] neg_lo:[1,0,0] neg_hi:[1,0,0]
	v_pk_fma_f32 v[70:71], v[116:117], v[202:203], v[70:71] op_sel_hi:[1,0,1]
	v_pk_fma_f32 v[66:67], v[112:113], v[202:203], v[66:67] op_sel_hi:[1,0,1]
	v_pk_fma_f32 v[64:65], v[64:65], v[216:217], v[128:129] op_sel_hi:[1,0,1]
	v_lshl_add_u64 v[80:81], v[80:81], 0, v[212:213]
	v_cvt_pk_bf16_f32 v72, v76, v77
	v_cvt_pk_bf16_f32 v73, v78, v79
	v_cvt_pk_bf16_f32 v74, v82, v83
	v_cvt_pk_bf16_f32 v75, v84, v85
	v_pk_fma_f32 v[70:71], v[70:71], v[216:217], v[138:139] op_sel_hi:[1,0,1]
	v_pk_fma_f32 v[68:69], v[68:69], v[216:217], v[136:137] op_sel_hi:[1,0,1]
	v_pk_fma_f32 v[66:67], v[66:67], v[216:217], v[130:131] op_sel_hi:[1,0,1]
	v_max_f32_e32 v64, 0, v64
	v_max_f32_e32 v65, 0, v65
	global_store_dwordx4 v[80:81], v[72:75], off nt
	v_max_f32_e32 v68, 0, v68
	v_max_f32_e32 v69, 0, v69
	v_pk_mul_f32 v[72:73], v[64:65], v[64:65]
	v_max_f32_e32 v64, 0, v70
	v_max_f32_e32 v66, 0, v66
	v_max_f32_e32 v65, 0, v71
	v_max_f32_e32 v67, 0, v67
	v_pk_fma_f32 v[56:57], v[148:149], v[206:207], v[56:57] op_sel_hi:[1,0,1] neg_lo:[1,0,0] neg_hi:[1,0,0]
	v_pk_mul_f32 v[68:69], v[68:69], v[68:69]
	v_pk_mul_f32 v[70:71], v[64:65], v[64:65]
	v_pk_mul_f32 v[74:75], v[66:67], v[66:67]
	v_pk_fma_f32 v[60:61], v[156:157], v[206:207], v[60:61] op_sel_hi:[1,0,1] neg_lo:[1,0,0] neg_hi:[1,0,0]
	v_pk_fma_f32 v[62:63], v[124:125], v[206:207], v[62:63] op_sel_hi:[1,0,1]
	v_pk_fma_f32 v[58:59], v[120:121], v[206:207], v[58:59] op_sel_hi:[1,0,1]
	v_pk_fma_f32 v[56:57], v[56:57], v[210:211], v[144:145] op_sel_hi:[1,0,1]
	v_cvt_pk_bf16_f32 v64, v68, v69
	v_cvt_pk_bf16_f32 v65, v70, v71
	v_cvt_pk_bf16_f32 v66, v72, v73
	v_cvt_pk_bf16_f32 v67, v74, v75
	v_pk_fma_f32 v[62:63], v[62:63], v[210:211], v[154:155] op_sel_hi:[1,0,1]
	v_pk_fma_f32 v[60:61], v[60:61], v[210:211], v[152:153] op_sel_hi:[1,0,1]
	v_pk_fma_f32 v[58:59], v[58:59], v[210:211], v[146:147] op_sel_hi:[1,0,1]
	v_max_f32_e32 v56, 0, v56
	v_max_f32_e32 v57, 0, v57
	global_store_dwordx4 v[80:81], v[64:67], off offset:256 nt
	v_max_f32_e32 v60, 0, v60
	v_max_f32_e32 v61, 0, v61
	v_lshlrev_b64 v[64:65], 13, v[180:181]
	v_pk_mul_f32 v[66:67], v[56:57], v[56:57]
	v_max_f32_e32 v56, 0, v62
	v_max_f32_e32 v58, 0, v58
	v_max_f32_e32 v57, 0, v63
	v_max_f32_e32 v59, 0, v59
	v_pk_fma_f32 v[48:49], v[132:133], v[206:207], v[48:49] op_sel_hi:[1,0,1] neg_lo:[1,0,0] neg_hi:[1,0,0]
	v_lshl_add_u64 v[64:65], s[24:25], 0, v[64:65]
	v_pk_mul_f32 v[60:61], v[60:61], v[60:61]
	v_pk_mul_f32 v[62:63], v[56:57], v[56:57]
	v_pk_mul_f32 v[68:69], v[58:59], v[58:59]
	v_pk_fma_f32 v[52:53], v[140:141], v[206:207], v[52:53] op_sel_hi:[1,0,1] neg_lo:[1,0,0] neg_hi:[1,0,0]
	v_pk_fma_f32 v[54:55], v[116:117], v[206:207], v[54:55] op_sel_hi:[1,0,1]
	v_pk_fma_f32 v[50:51], v[112:113], v[206:207], v[50:51] op_sel_hi:[1,0,1]
	v_pk_fma_f32 v[48:49], v[48:49], v[210:211], v[128:129] op_sel_hi:[1,0,1]
	v_lshl_add_u64 v[64:65], v[64:65], 0, v[212:213]
	v_cvt_pk_bf16_f32 v56, v60, v61
	v_cvt_pk_bf16_f32 v57, v62, v63
	v_cvt_pk_bf16_f32 v58, v66, v67
	v_cvt_pk_bf16_f32 v59, v68, v69
	v_pk_fma_f32 v[54:55], v[54:55], v[210:211], v[138:139] op_sel_hi:[1,0,1]
	v_pk_fma_f32 v[52:53], v[52:53], v[210:211], v[136:137] op_sel_hi:[1,0,1]
	v_pk_fma_f32 v[50:51], v[50:51], v[210:211], v[130:131] op_sel_hi:[1,0,1]
	v_max_f32_e32 v48, 0, v48
	v_max_f32_e32 v49, 0, v49
	global_store_dwordx4 v[64:65], v[56:59], off nt
	v_max_f32_e32 v52, 0, v52
	v_max_f32_e32 v53, 0, v53
	v_pk_mul_f32 v[56:57], v[48:49], v[48:49]
	v_max_f32_e32 v48, 0, v54
	v_max_f32_e32 v50, 0, v50
	v_max_f32_e32 v49, 0, v55
	v_max_f32_e32 v51, 0, v51
	v_pk_fma_f32 v[44:45], v[156:157], v[200:201], v[44:45] op_sel_hi:[1,0,1] neg_lo:[1,0,0] neg_hi:[1,0,0]
	v_pk_fma_f32 v[40:41], v[148:149], v[200:201], v[40:41] op_sel_hi:[1,0,1] neg_lo:[1,0,0] neg_hi:[1,0,0]
	v_pk_mul_f32 v[52:53], v[52:53], v[52:53]
	v_pk_mul_f32 v[54:55], v[48:49], v[48:49]
	v_pk_mul_f32 v[58:59], v[50:51], v[50:51]
	v_pk_fma_f32 v[46:47], v[124:125], v[200:201], v[46:47] op_sel_hi:[1,0,1]
	v_pk_fma_f32 v[44:45], v[44:45], v[204:205], v[152:153] op_sel_hi:[1,0,1]
	v_pk_fma_f32 v[42:43], v[120:121], v[200:201], v[42:43] op_sel_hi:[1,0,1]
	v_pk_fma_f32 v[40:41], v[40:41], v[204:205], v[144:145] op_sel_hi:[1,0,1]
	v_cvt_pk_bf16_f32 v48, v52, v53
	v_cvt_pk_bf16_f32 v49, v54, v55
	v_cvt_pk_bf16_f32 v50, v56, v57
	v_cvt_pk_bf16_f32 v51, v58, v59
	s_mov_b64 s[2:3], 0x120000
	v_pk_fma_f32 v[46:47], v[46:47], v[204:205], v[154:155] op_sel_hi:[1,0,1]
	v_pk_fma_f32 v[42:43], v[42:43], v[204:205], v[146:147] op_sel_hi:[1,0,1]
	v_max_f32_e32 v44, 0, v44
	v_max_f32_e32 v40, 0, v40
	v_max_f32_e32 v45, 0, v45
	v_max_f32_e32 v41, 0, v41
	global_store_dwordx4 v[64:65], v[48:51], off offset:256 nt
	v_pk_mul_f32 v[44:45], v[44:45], v[44:45]
	v_max_f32_e32 v42, 0, v42
	v_lshl_add_u64 v[48:49], v[188:189], 0, s[2:3]
	v_pk_mul_f32 v[50:51], v[40:41], v[40:41]
	v_max_f32_e32 v40, 0, v46
	v_max_f32_e32 v41, 0, v47
	v_max_f32_e32 v43, 0, v43
	s_mov_b32 s2, 0x120000
	v_pk_fma_f32 v[32:33], v[132:133], v[200:201], v[32:33] op_sel_hi:[1,0,1] neg_lo:[1,0,0] neg_hi:[1,0,0]
	v_pk_mul_f32 v[46:47], v[40:41], v[40:41]
	v_pk_mul_f32 v[52:53], v[42:43], v[42:43]
	v_cvt_pk_bf16_f32 v40, v44, v45
	v_add_co_u32_e32 v44, vcc, s2, v188
	v_pk_fma_f32 v[36:37], v[140:141], v[200:201], v[36:37] op_sel_hi:[1,0,1] neg_lo:[1,0,0] neg_hi:[1,0,0]
	v_pk_fma_f32 v[38:39], v[116:117], v[200:201], v[38:39] op_sel_hi:[1,0,1]
	v_pk_fma_f32 v[34:35], v[112:113], v[200:201], v[34:35] op_sel_hi:[1,0,1]
	v_pk_fma_f32 v[32:33], v[32:33], v[204:205], v[128:129] op_sel_hi:[1,0,1]
	v_cvt_pk_bf16_f32 v41, v46, v47
	v_cvt_pk_bf16_f32 v42, v50, v51
	v_cvt_pk_bf16_f32 v43, v52, v53
	v_addc_co_u32_e32 v45, vcc, 0, v189, vcc
	v_pk_fma_f32 v[38:39], v[38:39], v[204:205], v[138:139] op_sel_hi:[1,0,1]
	v_pk_fma_f32 v[36:37], v[36:37], v[204:205], v[136:137] op_sel_hi:[1,0,1]
	v_pk_fma_f32 v[34:35], v[34:35], v[204:205], v[130:131] op_sel_hi:[1,0,1]
	v_max_f32_e32 v32, 0, v32
	v_max_f32_e32 v33, 0, v33
	global_store_dwordx4 v[44:45], v[40:43], off nt
	v_max_f32_e32 v36, 0, v36
	v_max_f32_e32 v37, 0, v37
	v_pk_mul_f32 v[40:41], v[32:33], v[32:33]
	v_max_f32_e32 v32, 0, v38
	v_max_f32_e32 v34, 0, v34
	v_max_f32_e32 v33, 0, v39
	v_max_f32_e32 v35, 0, v35
	v_pk_fma_f32 v[28:29], v[156:157], v[190:191], v[28:29] op_sel_hi:[1,0,1] neg_lo:[1,0,0] neg_hi:[1,0,0]
	v_pk_fma_f32 v[24:25], v[148:149], v[190:191], v[24:25] op_sel_hi:[1,0,1] neg_lo:[1,0,0] neg_hi:[1,0,0]
	v_pk_mul_f32 v[36:37], v[36:37], v[36:37]
	v_pk_mul_f32 v[38:39], v[32:33], v[32:33]
	v_pk_mul_f32 v[42:43], v[34:35], v[34:35]
	v_pk_fma_f32 v[30:31], v[124:125], v[190:191], v[30:31] op_sel_hi:[1,0,1]
	v_pk_fma_f32 v[28:29], v[28:29], v[196:197], v[152:153] op_sel_hi:[1,0,1]
	v_pk_fma_f32 v[26:27], v[120:121], v[190:191], v[26:27] op_sel_hi:[1,0,1]
	v_pk_fma_f32 v[24:25], v[24:25], v[196:197], v[144:145] op_sel_hi:[1,0,1]
	v_cvt_pk_bf16_f32 v32, v36, v37
	v_cvt_pk_bf16_f32 v33, v38, v39
	v_cvt_pk_bf16_f32 v34, v40, v41
	v_cvt_pk_bf16_f32 v35, v42, v43
	s_mov_b64 s[2:3], 0x140000
	v_pk_fma_f32 v[30:31], v[30:31], v[196:197], v[154:155] op_sel_hi:[1,0,1]
	v_pk_fma_f32 v[26:27], v[26:27], v[196:197], v[146:147] op_sel_hi:[1,0,1]
	v_max_f32_e32 v28, 0, v28
	v_max_f32_e32 v24, 0, v24
	v_max_f32_e32 v29, 0, v29
	v_max_f32_e32 v25, 0, v25
	global_store_dwordx4 v[48:49], v[32:35], off offset:256 nt
	v_pk_mul_f32 v[28:29], v[28:29], v[28:29]
	v_max_f32_e32 v26, 0, v26
	v_lshl_add_u64 v[32:33], v[188:189], 0, s[2:3]
	v_pk_mul_f32 v[34:35], v[24:25], v[24:25]
	v_max_f32_e32 v24, 0, v30
	v_max_f32_e32 v25, 0, v31
	v_max_f32_e32 v27, 0, v27
	s_mov_b32 s2, 0x140000
	v_pk_fma_f32 v[16:17], v[132:133], v[190:191], v[16:17] op_sel_hi:[1,0,1] neg_lo:[1,0,0] neg_hi:[1,0,0]
	v_pk_mul_f32 v[30:31], v[24:25], v[24:25]
	v_pk_mul_f32 v[36:37], v[26:27], v[26:27]
	v_cvt_pk_bf16_f32 v24, v28, v29
	v_add_co_u32_e32 v28, vcc, s2, v188
	v_pk_fma_f32 v[20:21], v[140:141], v[190:191], v[20:21] op_sel_hi:[1,0,1] neg_lo:[1,0,0] neg_hi:[1,0,0]
	v_pk_fma_f32 v[22:23], v[116:117], v[190:191], v[22:23] op_sel_hi:[1,0,1]
	v_pk_fma_f32 v[18:19], v[112:113], v[190:191], v[18:19] op_sel_hi:[1,0,1]
	v_pk_fma_f32 v[16:17], v[16:17], v[196:197], v[128:129] op_sel_hi:[1,0,1]
	v_cvt_pk_bf16_f32 v25, v30, v31
	v_cvt_pk_bf16_f32 v26, v34, v35
	v_cvt_pk_bf16_f32 v27, v36, v37
	v_addc_co_u32_e32 v29, vcc, 0, v189, vcc
	v_pk_fma_f32 v[22:23], v[22:23], v[196:197], v[138:139] op_sel_hi:[1,0,1]
	v_pk_fma_f32 v[20:21], v[20:21], v[196:197], v[136:137] op_sel_hi:[1,0,1]
	v_pk_fma_f32 v[18:19], v[18:19], v[196:197], v[130:131] op_sel_hi:[1,0,1]
	v_max_f32_e32 v16, 0, v16
	v_max_f32_e32 v17, 0, v17
	global_store_dwordx4 v[28:29], v[24:27], off nt
	v_max_f32_e32 v20, 0, v20
	v_max_f32_e32 v21, 0, v21
	v_pk_mul_f32 v[24:25], v[16:17], v[16:17]
	v_max_f32_e32 v16, 0, v22
	v_max_f32_e32 v18, 0, v18
	v_max_f32_e32 v17, 0, v23
	v_max_f32_e32 v19, 0, v19
	v_pk_fma_f32 v[12:13], v[156:157], v[182:183], v[12:13] op_sel_hi:[1,0,1] neg_lo:[1,0,0] neg_hi:[1,0,0]
	v_pk_fma_f32 v[8:9], v[148:149], v[182:183], v[8:9] op_sel_hi:[1,0,1] neg_lo:[1,0,0] neg_hi:[1,0,0]
	v_pk_mul_f32 v[20:21], v[20:21], v[20:21]
	v_pk_mul_f32 v[22:23], v[16:17], v[16:17]
	v_pk_mul_f32 v[26:27], v[18:19], v[18:19]
	v_pk_fma_f32 v[14:15], v[124:125], v[182:183], v[14:15] op_sel_hi:[1,0,1]
	v_pk_fma_f32 v[12:13], v[12:13], v[186:187], v[152:153] op_sel_hi:[1,0,1]
	v_pk_fma_f32 v[10:11], v[120:121], v[182:183], v[10:11] op_sel_hi:[1,0,1]
	v_pk_fma_f32 v[8:9], v[8:9], v[186:187], v[144:145] op_sel_hi:[1,0,1]
	v_cvt_pk_bf16_f32 v16, v20, v21
	v_cvt_pk_bf16_f32 v17, v22, v23
	v_cvt_pk_bf16_f32 v18, v24, v25
	v_cvt_pk_bf16_f32 v19, v26, v27
	s_mov_b64 s[2:3], 0x160000
	v_pk_fma_f32 v[14:15], v[14:15], v[186:187], v[154:155] op_sel_hi:[1,0,1]
	v_pk_fma_f32 v[10:11], v[10:11], v[186:187], v[146:147] op_sel_hi:[1,0,1]
	v_max_f32_e32 v12, 0, v12
	v_max_f32_e32 v8, 0, v8
	v_max_f32_e32 v13, 0, v13
	v_max_f32_e32 v9, 0, v9
	global_store_dwordx4 v[32:33], v[16:19], off offset:256 nt
	v_pk_mul_f32 v[12:13], v[12:13], v[12:13]
	v_max_f32_e32 v10, 0, v10
	v_lshl_add_u64 v[16:17], v[188:189], 0, s[2:3]
	v_pk_mul_f32 v[18:19], v[8:9], v[8:9]
	v_max_f32_e32 v8, 0, v14
	v_max_f32_e32 v9, 0, v15
	v_max_f32_e32 v11, 0, v11
	s_mov_b32 s2, 0x160000
	v_pk_fma_f32 v[0:1], v[132:133], v[182:183], v[0:1] op_sel_hi:[1,0,1] neg_lo:[1,0,0] neg_hi:[1,0,0]
	v_pk_mul_f32 v[14:15], v[8:9], v[8:9]
	v_pk_mul_f32 v[20:21], v[10:11], v[10:11]
	v_cvt_pk_bf16_f32 v8, v12, v13
	v_add_co_u32_e32 v12, vcc, s2, v188
	v_pk_fma_f32 v[4:5], v[140:141], v[182:183], v[4:5] op_sel_hi:[1,0,1] neg_lo:[1,0,0] neg_hi:[1,0,0]
	v_pk_fma_f32 v[6:7], v[116:117], v[182:183], v[6:7] op_sel_hi:[1,0,1]
	v_pk_fma_f32 v[2:3], v[112:113], v[182:183], v[2:3] op_sel_hi:[1,0,1]
	v_pk_fma_f32 v[0:1], v[0:1], v[186:187], v[128:129] op_sel_hi:[1,0,1]
	v_cvt_pk_bf16_f32 v9, v14, v15
	v_cvt_pk_bf16_f32 v10, v18, v19
	v_cvt_pk_bf16_f32 v11, v20, v21
	v_addc_co_u32_e32 v13, vcc, 0, v189, vcc
	v_pk_fma_f32 v[6:7], v[6:7], v[186:187], v[138:139] op_sel_hi:[1,0,1]
	v_pk_fma_f32 v[4:5], v[4:5], v[186:187], v[136:137] op_sel_hi:[1,0,1]
	v_pk_fma_f32 v[2:3], v[2:3], v[186:187], v[130:131] op_sel_hi:[1,0,1]
	v_max_f32_e32 v0, 0, v0
	v_max_f32_e32 v1, 0, v1
	v_max_f32_e32 v126, 0, v126
	v_max_f32_e32 v127, 0, v127
	global_store_dwordx4 v[12:13], v[8:11], off nt
	v_max_f32_e32 v4, 0, v4
	v_max_f32_e32 v5, 0, v5
	v_pk_mul_f32 v[8:9], v[0:1], v[0:1]
	v_max_f32_e32 v0, 0, v6
	v_max_f32_e32 v2, 0, v2
	v_max_f32_e32 v1, 0, v7
	v_max_f32_e32 v3, 0, v3
	v_pk_mul_f32 v[126:127], v[126:127], v[126:127]
	v_pk_mul_f32 v[4:5], v[4:5], v[4:5]
	v_pk_mul_f32 v[6:7], v[0:1], v[0:1]
	v_pk_mul_f32 v[10:11], v[2:3], v[2:3]
	v_cvt_pk_bf16_f32 v224, v126, v127
	v_cvt_pk_bf16_f32 v0, v4, v5
	v_cvt_pk_bf16_f32 v1, v6, v7
	v_cvt_pk_bf16_f32 v2, v8, v9
	v_cvt_pk_bf16_f32 v3, v10, v11
	s_andn2_b64 vcc, exec, s[0:1]
	s_mov_b64 s[0:1], -1
	global_store_dwordx4 v[188:189], v[222:225], off offset:256 nt
	global_store_dwordx4 v[16:17], v[0:3], off offset:256 nt
	s_cbranch_vccnz .LBB0_603
	s_andn2_b64 vcc, exec, s[4:5]
	s_cbranch_vccnz .LBB0_602
	s_barrier
	s_branch .LBB0_602

.LBB0_1086:
	v_lshl_add_u32 v248, s4, 8, v169
	v_mov_b32_e32 v249, 0
	v_lshl_add_u64 v[248:249], v[248:249], 3, s[28:29]
	global_load_dwordx2 v[234:235], v[248:249], off
	global_load_dwordx2 v[236:237], v[248:249], off offset:128
	global_load_dwordx2 v[238:239], v[248:249], off offset:256
	global_load_dwordx2 v[240:241], v[248:249], off offset:384
	global_load_dwordx2 v[242:243], v[248:249], off offset:1024
	global_load_dwordx2 v[244:245], v[248:249], off offset:1152
	global_load_dwordx2 v[246:247], v[248:249], off offset:1280
	global_load_dwordx2 v[248:249], v[248:249], off offset:1408
	v_lshl_add_u32 v188, s4, 8, v169
	v_ashrrev_i32_e32 v189, 31, v188
	v_lshl_add_u64 v[128:129], v[188:189], 3, s[28:29]
	v_or_b32_e32 v194, 16, v188
	v_ashrrev_i32_e32 v195, 31, v194
	v_or_b32_e32 v192, 32, v188
	v_lshl_add_u64 v[128:129], v[194:195], 3, s[28:29]
	v_ashrrev_i32_e32 v193, 31, v192
	v_lshl_add_u64 v[130:131], v[192:193], 3, s[28:29]
	v_lshl_or_b32 v212, s5, 8, v187
	v_ashrrev_i32_e32 v213, 31, v212
	v_or_b32_e32 v184, 48, v188
	v_add_u32_e32 v180, 0x80, v188
	v_lshlrev_b64 v[128:129], 2, v[212:213]
	v_ashrrev_i32_e32 v185, 31, v184
	v_ashrrev_i32_e32 v181, 31, v180
	v_lshl_add_u64 v[130:131], s[30:31], 0, v[128:129]
	v_lshl_add_u64 v[136:137], s[34:35], 0, v[128:129]
	v_lshl_add_u64 v[200:201], v[184:185], 3, s[28:29]
	v_lshl_add_u64 v[202:203], v[180:181], 3, s[28:29]
	global_load_dwordx4 v[148:151], v[130:131], off offset:16
	global_load_dwordx4 v[156:159], v[130:131], off
	global_load_dwordx4 v[144:147], v[136:137], off offset:16
	global_load_dwordx4 v[152:155], v[136:137], off
	global_load_dwordx4 v[132:135], v[130:131], off offset:528
	global_load_dwordx4 v[140:143], v[130:131], off offset:512
	s_nop 0
	global_load_dwordx4 v[128:131], v[136:137], off offset:528
	s_nop 0
	global_load_dwordx4 v[136:139], v[136:137], off offset:512
	s_nop 0
	s_nop 0
	v_lshlrev_b64 v[212:213], 1, v[212:213]
	s_waitcnt vmcnt(0)
	v_pk_mul_f32 v[218:219], v[234:235], s[40:41] op_sel_hi:[1,0]
	s_nop 0
	v_fma_f32 v182, -v218, v218, v219
	v_add_f32_e32 v182, 0x3727c5ac, v182
	v_pk_mul_f32 v[208:209], v[236:237], s[40:41] op_sel_hi:[1,0]
	v_pk_mul_f32 v[196:197], v[238:239], s[40:41] op_sel_hi:[1,0]
	v_fma_f32 v183, -v208, v208, v209
	v_fma_f32 v186, -v196, v196, v197
	v_add_f32_e32 v183, 0x3727c5ac, v183
	v_add_f32_e32 v186, 0x3727c5ac, v186
	v_pk_mul_f32 v[206:207], v[242:243], s[40:41] op_sel_hi:[1,0]
	s_nop 0
	v_rsq_f32_e32 v222, v182
	v_rsq_f32_e32 v214, v183
	v_pk_mul_f32 v[202:203], v[240:241], s[40:41] op_sel_hi:[1,0]
	v_fma_f32 v200, -v202, v202, v203
	v_add_f32_e32 v200, 0x3727c5ac, v200
	v_rsq_f32_e32 v216, v200
	v_add_u32_e32 v182, 0x90, v188
	v_ashrrev_i32_e32 v183, 31, v182
	v_lshl_add_u64 v[182:183], v[182:183], 3, s[28:29]
	v_rsq_f32_e32 v220, v186
	v_pk_fma_f32 v[104:105], v[148:149], v[208:209], v[104:105] op_sel_hi:[1,0,1] neg_lo:[1,0,0] neg_hi:[1,0,0]
	v_pk_fma_f32 v[108:109], v[156:157], v[208:209], v[108:109] op_sel_hi:[1,0,1] neg_lo:[1,0,0] neg_hi:[1,0,0]
	v_pk_fma_f32 v[104:105], v[104:105], v[214:215], v[144:145] op_sel_hi:[1,0,1]
	v_add_u32_e32 v190, 0xa0, v188
	v_ashrrev_i32_e32 v191, 31, v190
	v_lshl_add_u64 v[190:191], v[190:191], 3, s[28:29]
	v_add_u32_e32 v200, 0xb0, v188
	v_ashrrev_i32_e32 v201, 31, v200
	v_lshl_add_u64 v[200:201], v[200:201], 3, s[28:29]
	v_fma_f32 v200, -v206, v206, v207
	v_add_f32_e32 v200, 0x3727c5ac, v200
	v_rsq_f32_e32 v210, v200
	v_lshlrev_b64 v[188:189], 13, v[188:189]
	v_lshl_add_u64 v[188:189], s[24:25], 0, v[188:189]
	v_lshl_add_u64 v[188:189], v[188:189], 0, v[212:213]
	v_pk_fma_f32 v[108:109], v[108:109], v[214:215], v[152:153] op_sel_hi:[1,0,1]
	v_max_f32_e32 v104, 0, v104
	v_pk_mul_f32 v[200:201], v[244:245], s[40:41] op_sel_hi:[1,0]
	v_fma_f32 v182, -v200, v200, v201
	v_add_f32_e32 v182, 0x3727c5ac, v182
	v_max_f32_e32 v105, 0, v105
	v_max_f32_e32 v108, 0, v108
	v_max_f32_e32 v109, 0, v109
	v_pk_fma_f32 v[96:97], v[132:133], v[208:209], v[96:97] op_sel_hi:[1,0,1] neg_lo:[1,0,0] neg_hi:[1,0,0]
	v_pk_mul_f32 v[108:109], v[108:109], v[108:109]
	v_pk_mul_f32 v[190:191], v[246:247], s[40:41] op_sel_hi:[1,0]
	v_pk_fma_f32 v[100:101], v[140:141], v[208:209], v[100:101] op_sel_hi:[1,0,1] neg_lo:[1,0,0] neg_hi:[1,0,0]
	v_fma_f32 v204, -v190, v190, v191
	v_add_f32_e32 v204, 0x3727c5ac, v204
	v_rsq_f32_e32 v198, v204
	v_pk_fma_f32 v[96:97], v[96:97], v[214:215], v[128:129] op_sel_hi:[1,0,1]
	v_pk_fma_f32 v[100:101], v[100:101], v[214:215], v[136:137] op_sel_hi:[1,0,1]
	v_max_f32_e32 v96, 0, v96
	v_max_f32_e32 v97, 0, v97
	v_rsq_f32_e32 v204, v182
	v_pk_mul_f32 v[182:183], v[248:249], s[40:41] op_sel_hi:[1,0]
	v_fma_f32 v224, -v182, v182, v183
	v_add_f32_e32 v224, 0x3727c5ac, v224
	v_rsq_f32_e32 v186, v224
	v_max_f32_e32 v100, 0, v100
	v_max_f32_e32 v101, 0, v101
	v_pk_fma_f32 v[88:89], v[148:149], v[196:197], v[88:89] op_sel_hi:[1,0,1] neg_lo:[1,0,0] neg_hi:[1,0,0]
	v_pk_mul_f32 v[100:101], v[100:101], v[100:101]
	v_pk_fma_f32 v[92:93], v[156:157], v[196:197], v[92:93] op_sel_hi:[1,0,1] neg_lo:[1,0,0] neg_hi:[1,0,0]
	v_pk_fma_f32 v[88:89], v[88:89], v[220:221], v[144:145] op_sel_hi:[1,0,1]
	v_pk_fma_f32 v[92:93], v[92:93], v[220:221], v[152:153] op_sel_hi:[1,0,1]
	v_max_f32_e32 v88, 0, v88
	v_pk_fma_f32 v[224:225], v[156:157], v[218:219], v[124:125] op_sel_hi:[1,0,1] neg_lo:[1,0,0] neg_hi:[1,0,0]
	v_xor_b32_e32 v125, 0x80000000, v159
	v_xor_b32_e32 v124, 0x80000000, v158
	v_pk_fma_f32 v[158:159], v[224:225], v[222:223], v[152:153] op_sel_hi:[1,0,1]
	v_pk_fma_f32 v[224:225], v[148:149], v[218:219], v[120:121] op_sel_hi:[1,0,1] neg_lo:[1,0,0] neg_hi:[1,0,0]
	v_xor_b32_e32 v121, 0x80000000, v151
	v_xor_b32_e32 v120, 0x80000000, v150
	v_pk_fma_f32 v[126:127], v[124:125], v[218:219], v[126:127] op_sel_hi:[1,0,1]
	v_pk_fma_f32 v[122:123], v[120:121], v[218:219], v[122:123] op_sel_hi:[1,0,1]
	v_pk_fma_f32 v[126:127], v[126:127], v[222:223], v[154:155] op_sel_hi:[1,0,1]
	v_pk_fma_f32 v[122:123], v[122:123], v[222:223], v[146:147] op_sel_hi:[1,0,1]
	v_max_f32_e32 v126, 0, v126
	v_max_f32_e32 v122, 0, v122
	v_max_f32_e32 v127, 0, v127
	v_max_f32_e32 v123, 0, v123
	v_pk_mul_f32 v[126:127], v[126:127], v[126:127]
	v_pk_mul_f32 v[122:123], v[122:123], v[122:123]
	v_pk_fma_f32 v[150:151], v[224:225], v[222:223], v[144:145] op_sel_hi:[1,0,1]
	v_cvt_pk_bf16_f32 v225, v126, v127
	v_cvt_pk_bf16_f32 v227, v122, v123
	v_pk_fma_f32 v[122:123], v[140:141], v[218:219], v[116:117] op_sel_hi:[1,0,1] neg_lo:[1,0,0] neg_hi:[1,0,0]
	v_xor_b32_e32 v117, 0x80000000, v143
	v_xor_b32_e32 v116, 0x80000000, v142
	v_pk_fma_f32 v[126:127], v[132:133], v[218:219], v[112:113] op_sel_hi:[1,0,1] neg_lo:[1,0,0] neg_hi:[1,0,0]
	v_xor_b32_e32 v113, 0x80000000, v135
	v_xor_b32_e32 v112, 0x80000000, v134
	v_pk_fma_f32 v[118:119], v[116:117], v[218:219], v[118:119] op_sel_hi:[1,0,1]
	v_pk_fma_f32 v[114:115], v[112:113], v[218:219], v[114:115] op_sel_hi:[1,0,1]
	v_max_f32_e32 v158, 0, v158
	v_max_f32_e32 v150, 0, v150
	v_max_f32_e32 v159, 0, v159
	v_max_f32_e32 v151, 0, v151
	v_pk_fma_f32 v[118:119], v[118:119], v[222:223], v[138:139] op_sel_hi:[1,0,1]
	v_pk_fma_f32 v[114:115], v[114:115], v[222:223], v[130:131] op_sel_hi:[1,0,1]
	v_pk_mul_f32 v[158:159], v[158:159], v[158:159]
	v_pk_mul_f32 v[150:151], v[150:151], v[150:151]
	v_pk_fma_f32 v[122:123], v[122:123], v[222:223], v[136:137] op_sel_hi:[1,0,1]
	v_max_f32_e32 v118, 0, v118
	v_max_f32_e32 v114, 0, v114
	v_max_f32_e32 v119, 0, v119
	v_max_f32_e32 v115, 0, v115
	v_pk_fma_f32 v[110:111], v[124:125], v[208:209], v[110:111] op_sel_hi:[1,0,1]
	v_pk_fma_f32 v[106:107], v[120:121], v[208:209], v[106:107] op_sel_hi:[1,0,1]
	v_cvt_pk_bf16_f32 v224, v158, v159
	v_cvt_pk_bf16_f32 v226, v150, v151
	v_max_f32_e32 v122, 0, v122
	v_max_f32_e32 v123, 0, v123
	v_pk_mul_f32 v[118:119], v[118:119], v[118:119]
	v_pk_mul_f32 v[114:115], v[114:115], v[114:115]
	v_pk_fma_f32 v[110:111], v[110:111], v[214:215], v[154:155] op_sel_hi:[1,0,1]
	v_pk_fma_f32 v[106:107], v[106:107], v[214:215], v[146:147] op_sel_hi:[1,0,1]
	global_store_dwordx4 v[188:189], v[224:227], off nt
	v_pk_fma_f32 v[126:127], v[126:127], v[222:223], v[128:129] op_sel_hi:[1,0,1]
	v_pk_mul_f32 v[122:123], v[122:123], v[122:123]
	v_cvt_pk_bf16_f32 v223, v118, v119
	v_cvt_pk_bf16_f32 v225, v114, v115
	v_lshlrev_b64 v[114:115], 13, v[194:195]
	v_pk_mul_f32 v[118:119], v[104:105], v[104:105]
	v_max_f32_e32 v104, 0, v110
	v_max_f32_e32 v106, 0, v106
	v_max_f32_e32 v105, 0, v111
	v_max_f32_e32 v107, 0, v107
	v_cvt_pk_bf16_f32 v222, v122, v123
	v_lshl_add_u64 v[114:115], s[24:25], 0, v[114:115]
	v_pk_mul_f32 v[110:111], v[104:105], v[104:105]
	v_pk_mul_f32 v[122:123], v[106:107], v[106:107]
	v_pk_fma_f32 v[102:103], v[116:117], v[208:209], v[102:103] op_sel_hi:[1,0,1]
	v_pk_fma_f32 v[98:99], v[112:113], v[208:209], v[98:99] op_sel_hi:[1,0,1]
	v_lshl_add_u64 v[114:115], v[114:115], 0, v[212:213]
	v_cvt_pk_bf16_f32 v104, v108, v109
	v_cvt_pk_bf16_f32 v105, v110, v111
	v_cvt_pk_bf16_f32 v106, v118, v119
	v_cvt_pk_bf16_f32 v107, v122, v123
	v_pk_fma_f32 v[102:103], v[102:103], v[214:215], v[138:139] op_sel_hi:[1,0,1]
	v_pk_fma_f32 v[98:99], v[98:99], v[214:215], v[130:131] op_sel_hi:[1,0,1]
	global_store_dwordx4 v[114:115], v[104:107], off nt
	v_max_f32_e32 v98, 0, v98
	v_max_f32_e32 v99, 0, v99
	v_pk_mul_f32 v[104:105], v[96:97], v[96:97]
	v_max_f32_e32 v96, 0, v102
	v_max_f32_e32 v97, 0, v103
	v_pk_mul_f32 v[102:103], v[96:97], v[96:97]
	v_pk_mul_f32 v[106:107], v[98:99], v[98:99]
	v_pk_fma_f32 v[94:95], v[124:125], v[196:197], v[94:95] op_sel_hi:[1,0,1]
	v_pk_fma_f32 v[90:91], v[120:121], v[196:197], v[90:91] op_sel_hi:[1,0,1]
	v_cvt_pk_bf16_f32 v96, v100, v101
	v_cvt_pk_bf16_f32 v97, v102, v103
	v_cvt_pk_bf16_f32 v98, v104, v105
	v_cvt_pk_bf16_f32 v99, v106, v107
	v_pk_fma_f32 v[94:95], v[94:95], v[220:221], v[154:155] op_sel_hi:[1,0,1]
	v_pk_fma_f32 v[90:91], v[90:91], v[220:221], v[146:147] op_sel_hi:[1,0,1]
	v_max_f32_e32 v89, 0, v89
	global_store_dwordx4 v[114:115], v[96:99], off offset:256 nt
	v_max_f32_e32 v92, 0, v92
	v_max_f32_e32 v93, 0, v93
	v_lshlrev_b64 v[96:97], 13, v[192:193]
	v_pk_mul_f32 v[98:99], v[88:89], v[88:89]
	v_max_f32_e32 v88, 0, v94
	v_max_f32_e32 v90, 0, v90
	v_max_f32_e32 v89, 0, v95
	v_max_f32_e32 v91, 0, v91
	v_pk_fma_f32 v[80:81], v[132:133], v[196:197], v[80:81] op_sel_hi:[1,0,1] neg_lo:[1,0,0] neg_hi:[1,0,0]
	v_lshl_add_u64 v[96:97], s[24:25], 0, v[96:97]
	v_pk_mul_f32 v[92:93], v[92:93], v[92:93]
	v_pk_mul_f32 v[94:95], v[88:89], v[88:89]
	v_pk_mul_f32 v[100:101], v[90:91], v[90:91]
	v_pk_fma_f32 v[84:85], v[140:141], v[196:197], v[84:85] op_sel_hi:[1,0,1] neg_lo:[1,0,0] neg_hi:[1,0,0]
	v_pk_fma_f32 v[86:87], v[116:117], v[196:197], v[86:87] op_sel_hi:[1,0,1]
	v_pk_fma_f32 v[82:83], v[112:113], v[196:197], v[82:83] op_sel_hi:[1,0,1]
	v_pk_fma_f32 v[80:81], v[80:81], v[220:221], v[128:129] op_sel_hi:[1,0,1]
	v_lshl_add_u64 v[96:97], v[96:97], 0, v[212:213]
	v_cvt_pk_bf16_f32 v88, v92, v93
	v_cvt_pk_bf16_f32 v89, v94, v95
	v_cvt_pk_bf16_f32 v90, v98, v99
	v_cvt_pk_bf16_f32 v91, v100, v101
	v_pk_fma_f32 v[86:87], v[86:87], v[220:221], v[138:139] op_sel_hi:[1,0,1]
	v_pk_fma_f32 v[84:85], v[84:85], v[220:221], v[136:137] op_sel_hi:[1,0,1]
	v_pk_fma_f32 v[82:83], v[82:83], v[220:221], v[130:131] op_sel_hi:[1,0,1]
	v_max_f32_e32 v80, 0, v80
	v_max_f32_e32 v81, 0, v81
	global_store_dwordx4 v[96:97], v[88:91], off nt
	v_max_f32_e32 v84, 0, v84
	v_max_f32_e32 v85, 0, v85
	v_pk_mul_f32 v[88:89], v[80:81], v[80:81]
	v_max_f32_e32 v80, 0, v86
	v_max_f32_e32 v82, 0, v82
	v_max_f32_e32 v81, 0, v87
	v_max_f32_e32 v83, 0, v83
	v_pk_fma_f32 v[72:73], v[148:149], v[202:203], v[72:73] op_sel_hi:[1,0,1] neg_lo:[1,0,0] neg_hi:[1,0,0]
	v_pk_mul_f32 v[84:85], v[84:85], v[84:85]
	v_pk_mul_f32 v[86:87], v[80:81], v[80:81]
	v_pk_mul_f32 v[90:91], v[82:83], v[82:83]
	v_pk_fma_f32 v[76:77], v[156:157], v[202:203], v[76:77] op_sel_hi:[1,0,1] neg_lo:[1,0,0] neg_hi:[1,0,0]
	v_pk_fma_f32 v[78:79], v[124:125], v[202:203], v[78:79] op_sel_hi:[1,0,1]
	v_pk_fma_f32 v[74:75], v[120:121], v[202:203], v[74:75] op_sel_hi:[1,0,1]
	v_pk_fma_f32 v[72:73], v[72:73], v[216:217], v[144:145] op_sel_hi:[1,0,1]
	v_cvt_pk_bf16_f32 v80, v84, v85
	v_cvt_pk_bf16_f32 v81, v86, v87
	v_cvt_pk_bf16_f32 v82, v88, v89
	v_cvt_pk_bf16_f32 v83, v90, v91
	v_pk_fma_f32 v[78:79], v[78:79], v[216:217], v[154:155] op_sel_hi:[1,0,1]
	v_pk_fma_f32 v[76:77], v[76:77], v[216:217], v[152:153] op_sel_hi:[1,0,1]
	v_pk_fma_f32 v[74:75], v[74:75], v[216:217], v[146:147] op_sel_hi:[1,0,1]
	v_max_f32_e32 v72, 0, v72
	v_max_f32_e32 v73, 0, v73
	global_store_dwordx4 v[96:97], v[80:83], off offset:256 nt
	v_max_f32_e32 v76, 0, v76
	v_max_f32_e32 v77, 0, v77
	v_lshlrev_b64 v[80:81], 13, v[184:185]
	v_pk_mul_f32 v[82:83], v[72:73], v[72:73]
	v_max_f32_e32 v72, 0, v78
	v_max_f32_e32 v74, 0, v74
	v_max_f32_e32 v73, 0, v79
	v_max_f32_e32 v75, 0, v75
	v_pk_fma_f32 v[64:65], v[132:133], v[202:203], v[64:65] op_sel_hi:[1,0,1] neg_lo:[1,0,0] neg_hi:[1,0,0]
	v_lshl_add_u64 v[80:81], s[24:25], 0, v[80:81]
	v_pk_mul_f32 v[76:77], v[76:77], v[76:77]
	v_pk_mul_f32 v[78:79], v[72:73], v[72:73]
	v_pk_mul_f32 v[84:85], v[74:75], v[74:75]
	v_pk_fma_f32 v[68:69], v[140:141], v[202:203], v[68:69] op_sel_hi:[1,0,1] neg_lo:[1,0,0] neg_hi:[1,0,0]
	v_pk_fma_f32 v[70:71], v[116:117], v[202:203], v[70:71] op_sel_hi:[1,0,1]
	v_pk_fma_f32 v[66:67], v[112:113], v[202:203], v[66:67] op_sel_hi:[1,0,1]
	v_pk_fma_f32 v[64:65], v[64:65], v[216:217], v[128:129] op_sel_hi:[1,0,1]
	v_lshl_add_u64 v[80:81], v[80:81], 0, v[212:213]
	v_cvt_pk_bf16_f32 v72, v76, v77
	v_cvt_pk_bf16_f32 v73, v78, v79
	v_cvt_pk_bf16_f32 v74, v82, v83
	v_cvt_pk_bf16_f32 v75, v84, v85
	v_pk_fma_f32 v[70:71], v[70:71], v[216:217], v[138:139] op_sel_hi:[1,0,1]
	v_pk_fma_f32 v[68:69], v[68:69], v[216:217], v[136:137] op_sel_hi:[1,0,1]
	v_pk_fma_f32 v[66:67], v[66:67], v[216:217], v[130:131] op_sel_hi:[1,0,1]
	v_max_f32_e32 v64, 0, v64
	v_max_f32_e32 v65, 0, v65
	global_store_dwordx4 v[80:81], v[72:75], off nt
	v_max_f32_e32 v68, 0, v68
	v_max_f32_e32 v69, 0, v69
	v_pk_mul_f32 v[72:73], v[64:65], v[64:65]
	v_max_f32_e32 v64, 0, v70
	v_max_f32_e32 v66, 0, v66
	v_max_f32_e32 v65, 0, v71
	v_max_f32_e32 v67, 0, v67
	v_pk_fma_f32 v[56:57], v[148:149], v[206:207], v[56:57] op_sel_hi:[1,0,1] neg_lo:[1,0,0] neg_hi:[1,0,0]
	v_pk_mul_f32 v[68:69], v[68:69], v[68:69]
	v_pk_mul_f32 v[70:71], v[64:65], v[64:65]
	v_pk_mul_f32 v[74:75], v[66:67], v[66:67]
	v_pk_fma_f32 v[60:61], v[156:157], v[206:207], v[60:61] op_sel_hi:[1,0,1] neg_lo:[1,0,0] neg_hi:[1,0,0]
	v_pk_fma_f32 v[62:63], v[124:125], v[206:207], v[62:63] op_sel_hi:[1,0,1]
	v_pk_fma_f32 v[58:59], v[120:121], v[206:207], v[58:59] op_sel_hi:[1,0,1]
	v_pk_fma_f32 v[56:57], v[56:57], v[210:211], v[144:145] op_sel_hi:[1,0,1]
	v_cvt_pk_bf16_f32 v64, v68, v69
	v_cvt_pk_bf16_f32 v65, v70, v71
	v_cvt_pk_bf16_f32 v66, v72, v73
	v_cvt_pk_bf16_f32 v67, v74, v75
	v_pk_fma_f32 v[62:63], v[62:63], v[210:211], v[154:155] op_sel_hi:[1,0,1]
	v_pk_fma_f32 v[60:61], v[60:61], v[210:211], v[152:153] op_sel_hi:[1,0,1]
	v_pk_fma_f32 v[58:59], v[58:59], v[210:211], v[146:147] op_sel_hi:[1,0,1]
	v_max_f32_e32 v56, 0, v56
	v_max_f32_e32 v57, 0, v57
	global_store_dwordx4 v[80:81], v[64:67], off offset:256 nt
	v_max_f32_e32 v60, 0, v60
	v_max_f32_e32 v61, 0, v61
	v_lshlrev_b64 v[64:65], 13, v[180:181]
	v_pk_mul_f32 v[66:67], v[56:57], v[56:57]
	v_max_f32_e32 v56, 0, v62
	v_max_f32_e32 v58, 0, v58
	v_max_f32_e32 v57, 0, v63
	v_max_f32_e32 v59, 0, v59
	v_pk_fma_f32 v[48:49], v[132:133], v[206:207], v[48:49] op_sel_hi:[1,0,1] neg_lo:[1,0,0] neg_hi:[1,0,0]
	v_lshl_add_u64 v[64:65], s[24:25], 0, v[64:65]
	v_pk_mul_f32 v[60:61], v[60:61], v[60:61]
	v_pk_mul_f32 v[62:63], v[56:57], v[56:57]
	v_pk_mul_f32 v[68:69], v[58:59], v[58:59]
	v_pk_fma_f32 v[52:53], v[140:141], v[206:207], v[52:53] op_sel_hi:[1,0,1] neg_lo:[1,0,0] neg_hi:[1,0,0]
	v_pk_fma_f32 v[54:55], v[116:117], v[206:207], v[54:55] op_sel_hi:[1,0,1]
	v_pk_fma_f32 v[50:51], v[112:113], v[206:207], v[50:51] op_sel_hi:[1,0,1]
	v_pk_fma_f32 v[48:49], v[48:49], v[210:211], v[128:129] op_sel_hi:[1,0,1]
	v_lshl_add_u64 v[64:65], v[64:65], 0, v[212:213]
	v_cvt_pk_bf16_f32 v56, v60, v61
	v_cvt_pk_bf16_f32 v57, v62, v63
	v_cvt_pk_bf16_f32 v58, v66, v67
	v_cvt_pk_bf16_f32 v59, v68, v69
	v_pk_fma_f32 v[54:55], v[54:55], v[210:211], v[138:139] op_sel_hi:[1,0,1]
	v_pk_fma_f32 v[52:53], v[52:53], v[210:211], v[136:137] op_sel_hi:[1,0,1]
	v_pk_fma_f32 v[50:51], v[50:51], v[210:211], v[130:131] op_sel_hi:[1,0,1]
	v_max_f32_e32 v48, 0, v48
	v_max_f32_e32 v49, 0, v49
	global_store_dwordx4 v[64:65], v[56:59], off nt
	v_max_f32_e32 v52, 0, v52
	v_max_f32_e32 v53, 0, v53
	v_pk_mul_f32 v[56:57], v[48:49], v[48:49]
	v_max_f32_e32 v48, 0, v54
	v_max_f32_e32 v50, 0, v50
	v_max_f32_e32 v49, 0, v55
	v_max_f32_e32 v51, 0, v51
	v_pk_fma_f32 v[44:45], v[156:157], v[200:201], v[44:45] op_sel_hi:[1,0,1] neg_lo:[1,0,0] neg_hi:[1,0,0]
	v_pk_fma_f32 v[40:41], v[148:149], v[200:201], v[40:41] op_sel_hi:[1,0,1] neg_lo:[1,0,0] neg_hi:[1,0,0]
	v_pk_mul_f32 v[52:53], v[52:53], v[52:53]
	v_pk_mul_f32 v[54:55], v[48:49], v[48:49]
	v_pk_mul_f32 v[58:59], v[50:51], v[50:51]
	v_pk_fma_f32 v[46:47], v[124:125], v[200:201], v[46:47] op_sel_hi:[1,0,1]
	v_pk_fma_f32 v[44:45], v[44:45], v[204:205], v[152:153] op_sel_hi:[1,0,1]
	v_pk_fma_f32 v[42:43], v[120:121], v[200:201], v[42:43] op_sel_hi:[1,0,1]
	v_pk_fma_f32 v[40:41], v[40:41], v[204:205], v[144:145] op_sel_hi:[1,0,1]
	v_cvt_pk_bf16_f32 v48, v52, v53
	v_cvt_pk_bf16_f32 v49, v54, v55
	v_cvt_pk_bf16_f32 v50, v56, v57
	v_cvt_pk_bf16_f32 v51, v58, v59
	v_pk_fma_f32 v[46:47], v[46:47], v[204:205], v[154:155] op_sel_hi:[1,0,1]
	v_pk_fma_f32 v[42:43], v[42:43], v[204:205], v[146:147] op_sel_hi:[1,0,1]
	v_max_f32_e32 v44, 0, v44
	v_max_f32_e32 v40, 0, v40
	v_max_f32_e32 v45, 0, v45
	v_max_f32_e32 v41, 0, v41
	global_store_dwordx4 v[64:65], v[48:51], off offset:256 nt
	v_pk_mul_f32 v[44:45], v[44:45], v[44:45]
	v_max_f32_e32 v42, 0, v42
	v_pk_mul_f32 v[50:51], v[40:41], v[40:41]
	v_max_f32_e32 v40, 0, v46
	v_max_f32_e32 v41, 0, v47
	v_max_f32_e32 v43, 0, v43
	v_pk_fma_f32 v[32:33], v[132:133], v[200:201], v[32:33] op_sel_hi:[1,0,1] neg_lo:[1,0,0] neg_hi:[1,0,0]
	v_pk_mul_f32 v[46:47], v[40:41], v[40:41]
	v_pk_mul_f32 v[52:53], v[42:43], v[42:43]
	v_cvt_pk_bf16_f32 v40, v44, v45
	v_add_co_u32_e32 v44, vcc, s67, v188
	v_pk_fma_f32 v[36:37], v[140:141], v[200:201], v[36:37] op_sel_hi:[1,0,1] neg_lo:[1,0,0] neg_hi:[1,0,0]
	v_pk_fma_f32 v[38:39], v[116:117], v[200:201], v[38:39] op_sel_hi:[1,0,1]
	v_pk_fma_f32 v[34:35], v[112:113], v[200:201], v[34:35] op_sel_hi:[1,0,1]
	v_pk_fma_f32 v[32:33], v[32:33], v[204:205], v[128:129] op_sel_hi:[1,0,1]
	v_cvt_pk_bf16_f32 v41, v46, v47
	v_cvt_pk_bf16_f32 v42, v50, v51
	v_cvt_pk_bf16_f32 v43, v52, v53
	v_addc_co_u32_e32 v45, vcc, 0, v189, vcc
	v_pk_fma_f32 v[38:39], v[38:39], v[204:205], v[138:139] op_sel_hi:[1,0,1]
	v_pk_fma_f32 v[36:37], v[36:37], v[204:205], v[136:137] op_sel_hi:[1,0,1]
	v_pk_fma_f32 v[34:35], v[34:35], v[204:205], v[130:131] op_sel_hi:[1,0,1]
	v_max_f32_e32 v32, 0, v32
	v_max_f32_e32 v33, 0, v33
	global_store_dwordx4 v[44:45], v[40:43], off nt
	v_max_f32_e32 v36, 0, v36
	v_max_f32_e32 v37, 0, v37
	v_pk_mul_f32 v[40:41], v[32:33], v[32:33]
	v_max_f32_e32 v32, 0, v38
	v_max_f32_e32 v34, 0, v34
	v_max_f32_e32 v33, 0, v39
	v_max_f32_e32 v35, 0, v35
	v_pk_fma_f32 v[28:29], v[156:157], v[190:191], v[28:29] op_sel_hi:[1,0,1] neg_lo:[1,0,0] neg_hi:[1,0,0]
	v_pk_fma_f32 v[24:25], v[148:149], v[190:191], v[24:25] op_sel_hi:[1,0,1] neg_lo:[1,0,0] neg_hi:[1,0,0]
	v_pk_mul_f32 v[36:37], v[36:37], v[36:37]
	v_pk_mul_f32 v[38:39], v[32:33], v[32:33]
	v_pk_mul_f32 v[42:43], v[34:35], v[34:35]
	v_pk_fma_f32 v[30:31], v[124:125], v[190:191], v[30:31] op_sel_hi:[1,0,1]
	v_pk_fma_f32 v[28:29], v[28:29], v[198:199], v[152:153] op_sel_hi:[1,0,1]
	v_pk_fma_f32 v[26:27], v[120:121], v[190:191], v[26:27] op_sel_hi:[1,0,1]
	v_pk_fma_f32 v[24:25], v[24:25], v[198:199], v[144:145] op_sel_hi:[1,0,1]
	v_lshl_add_u64 v[48:49], v[188:189], 0, s[42:43]
	v_cvt_pk_bf16_f32 v32, v36, v37
	v_cvt_pk_bf16_f32 v33, v38, v39
	v_cvt_pk_bf16_f32 v34, v40, v41
	v_cvt_pk_bf16_f32 v35, v42, v43
	v_pk_fma_f32 v[30:31], v[30:31], v[198:199], v[154:155] op_sel_hi:[1,0,1]
	v_pk_fma_f32 v[26:27], v[26:27], v[198:199], v[146:147] op_sel_hi:[1,0,1]
	v_max_f32_e32 v28, 0, v28
	v_max_f32_e32 v24, 0, v24
	v_max_f32_e32 v29, 0, v29
	v_max_f32_e32 v25, 0, v25
	global_store_dwordx4 v[48:49], v[32:35], off offset:256 nt
	v_pk_mul_f32 v[28:29], v[28:29], v[28:29]
	v_max_f32_e32 v26, 0, v26
	v_pk_mul_f32 v[34:35], v[24:25], v[24:25]
	v_max_f32_e32 v24, 0, v30
	v_max_f32_e32 v25, 0, v31
	v_max_f32_e32 v27, 0, v27
	v_pk_fma_f32 v[16:17], v[132:133], v[190:191], v[16:17] op_sel_hi:[1,0,1] neg_lo:[1,0,0] neg_hi:[1,0,0]
	v_pk_mul_f32 v[30:31], v[24:25], v[24:25]
	v_pk_mul_f32 v[36:37], v[26:27], v[26:27]
	v_cvt_pk_bf16_f32 v24, v28, v29
	v_add_co_u32_e32 v28, vcc, s68, v188
	v_pk_fma_f32 v[20:21], v[140:141], v[190:191], v[20:21] op_sel_hi:[1,0,1] neg_lo:[1,0,0] neg_hi:[1,0,0]
	v_pk_fma_f32 v[22:23], v[116:117], v[190:191], v[22:23] op_sel_hi:[1,0,1]
	v_pk_fma_f32 v[18:19], v[112:113], v[190:191], v[18:19] op_sel_hi:[1,0,1]
	v_pk_fma_f32 v[16:17], v[16:17], v[198:199], v[128:129] op_sel_hi:[1,0,1]
	v_cvt_pk_bf16_f32 v25, v30, v31
	v_cvt_pk_bf16_f32 v26, v34, v35
	v_cvt_pk_bf16_f32 v27, v36, v37
	v_addc_co_u32_e32 v29, vcc, 0, v189, vcc
	v_pk_fma_f32 v[22:23], v[22:23], v[198:199], v[138:139] op_sel_hi:[1,0,1]
	v_pk_fma_f32 v[20:21], v[20:21], v[198:199], v[136:137] op_sel_hi:[1,0,1]
	v_pk_fma_f32 v[18:19], v[18:19], v[198:199], v[130:131] op_sel_hi:[1,0,1]
	v_max_f32_e32 v16, 0, v16
	v_max_f32_e32 v17, 0, v17
	global_store_dwordx4 v[28:29], v[24:27], off nt
	v_max_f32_e32 v20, 0, v20
	v_max_f32_e32 v21, 0, v21
	v_pk_mul_f32 v[24:25], v[16:17], v[16:17]
	v_max_f32_e32 v16, 0, v22
	v_max_f32_e32 v18, 0, v18
	v_max_f32_e32 v17, 0, v23
	v_max_f32_e32 v19, 0, v19
	v_pk_fma_f32 v[12:13], v[156:157], v[182:183], v[12:13] op_sel_hi:[1,0,1] neg_lo:[1,0,0] neg_hi:[1,0,0]
	v_pk_fma_f32 v[8:9], v[148:149], v[182:183], v[8:9] op_sel_hi:[1,0,1] neg_lo:[1,0,0] neg_hi:[1,0,0]
	v_pk_mul_f32 v[20:21], v[20:21], v[20:21]
	v_pk_mul_f32 v[22:23], v[16:17], v[16:17]
	v_pk_mul_f32 v[26:27], v[18:19], v[18:19]
	v_pk_fma_f32 v[14:15], v[124:125], v[182:183], v[14:15] op_sel_hi:[1,0,1]
	v_pk_fma_f32 v[12:13], v[12:13], v[186:187], v[152:153] op_sel_hi:[1,0,1]
	v_pk_fma_f32 v[10:11], v[120:121], v[182:183], v[10:11] op_sel_hi:[1,0,1]
	v_pk_fma_f32 v[8:9], v[8:9], v[186:187], v[144:145] op_sel_hi:[1,0,1]
	v_lshl_add_u64 v[32:33], v[188:189], 0, s[44:45]
	v_cvt_pk_bf16_f32 v16, v20, v21
	v_cvt_pk_bf16_f32 v17, v22, v23
	v_cvt_pk_bf16_f32 v18, v24, v25
	v_cvt_pk_bf16_f32 v19, v26, v27
	v_pk_fma_f32 v[14:15], v[14:15], v[186:187], v[154:155] op_sel_hi:[1,0,1]
	v_pk_fma_f32 v[10:11], v[10:11], v[186:187], v[146:147] op_sel_hi:[1,0,1]
	v_max_f32_e32 v12, 0, v12
	v_max_f32_e32 v8, 0, v8
	v_max_f32_e32 v13, 0, v13
	v_max_f32_e32 v9, 0, v9
	global_store_dwordx4 v[32:33], v[16:19], off offset:256 nt
	v_pk_mul_f32 v[12:13], v[12:13], v[12:13]
	v_max_f32_e32 v10, 0, v10
	v_pk_mul_f32 v[18:19], v[8:9], v[8:9]
	v_max_f32_e32 v8, 0, v14
	v_max_f32_e32 v9, 0, v15
	v_max_f32_e32 v11, 0, v11
	v_pk_fma_f32 v[0:1], v[132:133], v[182:183], v[0:1] op_sel_hi:[1,0,1] neg_lo:[1,0,0] neg_hi:[1,0,0]
	v_pk_mul_f32 v[14:15], v[8:9], v[8:9]
	v_pk_mul_f32 v[20:21], v[10:11], v[10:11]
	v_cvt_pk_bf16_f32 v8, v12, v13
	v_add_co_u32_e32 v12, vcc, s69, v188
	v_pk_fma_f32 v[4:5], v[140:141], v[182:183], v[4:5] op_sel_hi:[1,0,1] neg_lo:[1,0,0] neg_hi:[1,0,0]
	v_pk_fma_f32 v[6:7], v[116:117], v[182:183], v[6:7] op_sel_hi:[1,0,1]
	v_pk_fma_f32 v[2:3], v[112:113], v[182:183], v[2:3] op_sel_hi:[1,0,1]
	v_pk_fma_f32 v[0:1], v[0:1], v[186:187], v[128:129] op_sel_hi:[1,0,1]
	v_cvt_pk_bf16_f32 v9, v14, v15
	v_cvt_pk_bf16_f32 v10, v18, v19
	v_cvt_pk_bf16_f32 v11, v20, v21
	v_addc_co_u32_e32 v13, vcc, 0, v189, vcc
	v_pk_fma_f32 v[6:7], v[6:7], v[186:187], v[138:139] op_sel_hi:[1,0,1]
	v_pk_fma_f32 v[4:5], v[4:5], v[186:187], v[136:137] op_sel_hi:[1,0,1]
	v_pk_fma_f32 v[2:3], v[2:3], v[186:187], v[130:131] op_sel_hi:[1,0,1]
	v_max_f32_e32 v0, 0, v0
	v_max_f32_e32 v1, 0, v1
	v_max_f32_e32 v126, 0, v126
	v_max_f32_e32 v127, 0, v127
	global_store_dwordx4 v[12:13], v[8:11], off nt
	v_max_f32_e32 v4, 0, v4
	v_max_f32_e32 v5, 0, v5
	v_pk_mul_f32 v[8:9], v[0:1], v[0:1]
	v_max_f32_e32 v0, 0, v6
	v_max_f32_e32 v2, 0, v2
	v_max_f32_e32 v1, 0, v7
	v_max_f32_e32 v3, 0, v3
	v_pk_mul_f32 v[126:127], v[126:127], v[126:127]
	v_pk_mul_f32 v[4:5], v[4:5], v[4:5]
	v_pk_mul_f32 v[6:7], v[0:1], v[0:1]
	v_pk_mul_f32 v[10:11], v[2:3], v[2:3]
	v_cvt_pk_bf16_f32 v224, v126, v127
	v_lshl_add_u64 v[16:17], v[188:189], 0, s[46:47]
	v_cvt_pk_bf16_f32 v0, v4, v5
	v_cvt_pk_bf16_f32 v1, v6, v7
	v_cvt_pk_bf16_f32 v2, v8, v9
	v_cvt_pk_bf16_f32 v3, v10, v11
	s_andn2_b64 vcc, exec, s[0:1]
	s_mov_b64 s[0:1], -1
	global_store_dwordx4 v[188:189], v[222:225], off offset:256 nt
	global_store_dwordx4 v[16:17], v[0:3], off offset:256 nt
	s_cbranch_vccnz .LBB0_1075
	s_andn2_b64 vcc, exec, s[10:11]
	s_cbranch_vccnz .LBB0_1074
	s_barrier
	s_branch .LBB0_1074
